# pw1 (conformer GLU) GEMM K-loop also peeled with SrcC=0 first iteration (all 12 GEMM loops now skip accumulator zeroing)
# speedup vs baseline: 1.0025x; 1.0025x over previous
; #define PG8_STAGE(bufoff, gbase, voff) do { _Pragma("unroll") for (int _i = 0; _i < 2; ++_i) \
;         __builtin_amdgcn_global_load_lds((const unsigned*)((const char*)(gbase) + (voff)[_i]), (PG8_LAS unsigned*)(lds + (bufoff) + ldsw + _i * 8192), 16, 0, 0); } while (0)
; #define PG8_LDA(dst, b, h) do { _Pragma("unroll") for (int m = 0; m < 4; ++m) _Pragma("unroll") for (int k = 0; k < 2; ++k) dst[m][k] = *(const PG8_LAS bf16x8*)(lds + PG8_SA(b, h) + aoff + m * 2048 + k * 1024); } while (0)
; #define PG8_LDB(dst, b, h) do { _Pragma("unroll") for (int n = 0; n < 2; ++n) _Pragma("unroll") for (int k = 0; k < 2; ++k) dst[n][k] = *(const PG8_LAS bf16x8*)(lds + PG8_SB(b, h) + boff + n * 2048 + k * 1024); } while (0)
; #define PG8_WAIT_V(n) asm volatile("s_waitcnt vmcnt(" #n ")" ::: "memory")
; #define PG8_WAIT_L(n) asm volatile("s_waitcnt lgkmcnt(" #n ")" ::: "memory")
; #define PG8_BAR __builtin_amdgcn_s_barrier()
; #define PG8_SCHED __builtin_amdgcn_sched_barrier(0)
; template <class Epi, class Sched, bool ALIGN_EPI = false, bool SP2 = false, bool TA = true>
; __device__ __forceinline__ void gemm_phase(PG8_LAS unsigned char* lds, const Gemm g, const Sched& S, const Epi& E) {
;     ...
;         const char* nA = has_next ? (const char*)g.A + (size_t)nxt.pm * tstep : cA; const char* nB = has_next ? (const char*)g.Bt + (size_t)nxt.pn * tstep : cB;
; #pragma unroll 1
;         for (int t = 0; t < nt; t += 2) {
;             const bool last = (t == nt - 2);
;             const char* a1 = cA + (size_t)(t + 1) * kstep;
;             const char* a2 = last ? nA : cA + (size_t)(t + 2) * kstep; const char* b2 = last ? nB : cB + (size_t)(t + 2) * kstepB;
;             const char* a3 = a2 + kstep; const char* b3 = b2 + kstepB;
;             if (last && has_next) S.a_ready(nxt);
;             if constexpr (SP2) {
;             PG8_LDB(B0, 0, 0); PG8_LDB(B1, 0, 1); PG8_SCHED; PG8_LDA(At, 0, 0); PG8_STAGE(PG8_SA(1, 1), a1 + hstep, voffA);
;             PG8_WAIT_V(8); PG8_WAIT_L(0); PG8_BAR; PG8_MMA(0, 0, At, B0); PG8_MMA(0, 1, At, B1); PG8_BAR; PG8_SCHED;
;             PG8_LDA(At, 0, 1); PG8_STAGE(PG8_SB(0, 0), b2, voffB); PG8_STAGE(PG8_SB(0, 1), b2 + hstep, voffB); PG8_STAGE(PG8_SA(0, 0), a2, voffA);
;             PG8_WAIT_V(8); PG8_WAIT_L(0); PG8_BAR; PG8_MMA(1, 0, At, B0); PG8_MMA(1, 1, At, B1); PG8_BAR; PG8_SCHED;
.LBB0_487:
	s_ashr_i32 s27, s26, 31
	s_lshl_b64 s[38:39], s[26:27], 19
	s_add_u32 s70, s34, s38
	s_addc_u32 s71, s35, s39
	s_and_b64 s[38:39], s[4:5], exec
	s_cselect_b32 s38, s71, s87
	s_cselect_b32 s39, s70, s86
	s_ashr_i32 s77, s76, 31
	s_lshl_b64 s[40:41], s[76:77], 19
	s_add_u32 s72, s90, s40
	s_addc_u32 s73, s91, s41
	s_and_b64 s[40:41], s[4:5], exec
	s_cselect_b32 s40, s73, s89
	s_cselect_b32 s41, s72, s88
	s_add_u32 s86, s86, 0x44000
	s_addc_u32 s87, s87, 0
	s_add_u32 s42, s88, 0x8000
	s_addc_u32 s43, s89, 0
	s_mov_b32 s59, -2
	s_waitcnt lgkmcnt(0)
	ds_read_b128 v[56:59], v167
	ds_read_b128 v[64:67], v167 offset:1024
	ds_read_b128 v[72:75], v167 offset:2048
	ds_read_b128 v[76:79], v167 offset:3072
	ds_read_b128 v[150:153], v168
	ds_read_b128 v[154:157], v168 offset:1024
	ds_read_b128 v[158:161], v168 offset:2048
	ds_read_b128 v[172:175], v168 offset:3072
	s_add_u32 s61, s86, 0xfffc4000
	s_addc_u32 s75, s87, -1
	s_cmp_eq_u32 s59, 12
	s_cselect_b32 s89, s38, s75
	s_cselect_b32 s88, s39, s61
	s_cselect_b32 s97, s40, s43
	s_cselect_b32 s96, s41, s42
	v_lshl_add_u64 v[210:211], s[86:87], 0, v[144:145]
	s_add_i32 m0, s84, 0xc000
	ds_read_b128 v[176:179], v169
	ds_read_b128 v[180:183], v169 offset:1024
	ds_read_b128 v[184:187], v169 offset:2048
	ds_read_b128 v[188:191], v169 offset:3072
	ds_read_b128 v[192:195], v169 offset:4096
	ds_read_b128 v[196:199], v169 offset:5120
	ds_read_b128 v[200:203], v169 offset:6144
	ds_read_b128 v[204:207], v169 offset:7168
	global_load_lds_dwordx4 v[210:211], off
	v_lshl_add_u64 v[210:211], v[210:211], 0, s[6:7]
	s_add_i32 m0, s84, 0xe000
	s_nop 0
	global_load_lds_dwordx4 v[210:211], off
	s_waitcnt vmcnt(8)
	s_waitcnt lgkmcnt(0)
	s_barrier
	s_setprio 1
	s_waitcnt lgkmcnt(0)
	v_mfma_f32_16x16x32_bf16 v[140:143], v[56:59], v[176:179], 0
	v_mfma_f32_16x16x32_bf16 v[136:139], v[72:75], v[176:179], 0
	v_mfma_f32_16x16x32_bf16 v[124:127], v[56:59], v[184:187], 0
	v_mfma_f32_16x16x32_bf16 v[116:119], v[72:75], v[184:187], 0
	v_mfma_f32_16x16x32_bf16 v[108:111], v[56:59], v[192:195], 0
	v_mfma_f32_16x16x32_bf16 v[100:103], v[72:75], v[192:195], 0
	v_mfma_f32_16x16x32_bf16 v[92:95], v[56:59], v[200:203], 0
	v_mfma_f32_16x16x32_bf16 v[84:87], v[72:75], v[200:203], 0
	v_mfma_f32_16x16x32_bf16 v[140:143], v[64:67], v[180:183], v[140:143]
	v_mfma_f32_16x16x32_bf16 v[136:139], v[76:79], v[180:183], v[136:139]
	v_mfma_f32_16x16x32_bf16 v[124:127], v[64:67], v[188:191], v[124:127]
	v_mfma_f32_16x16x32_bf16 v[116:119], v[76:79], v[188:191], v[116:119]
	v_mfma_f32_16x16x32_bf16 v[108:111], v[64:67], v[196:199], v[108:111]
	v_mfma_f32_16x16x32_bf16 v[100:103], v[76:79], v[196:199], v[100:103]
	v_mfma_f32_16x16x32_bf16 v[92:95], v[64:67], v[204:207], v[92:95]
	v_mfma_f32_16x16x32_bf16 v[84:87], v[76:79], v[204:207], v[84:87]
	s_setprio 0
	s_setprio 1
	v_mfma_f32_16x16x32_bf16 v[132:135], v[150:153], v[176:179], 0
	v_mfma_f32_16x16x32_bf16 v[128:131], v[158:161], v[176:179], 0
	v_mfma_f32_16x16x32_bf16 v[120:123], v[150:153], v[184:187], 0
	v_mfma_f32_16x16x32_bf16 v[112:115], v[158:161], v[184:187], 0
	v_mfma_f32_16x16x32_bf16 v[104:107], v[150:153], v[192:195], 0
	v_mfma_f32_16x16x32_bf16 v[96:99], v[158:161], v[192:195], 0
	v_mfma_f32_16x16x32_bf16 v[88:91], v[150:153], v[200:203], 0
	v_mfma_f32_16x16x32_bf16 v[80:83], v[158:161], v[200:203], 0
	v_mfma_f32_16x16x32_bf16 v[132:135], v[154:157], v[180:183], v[132:135]
	v_mfma_f32_16x16x32_bf16 v[128:131], v[172:175], v[180:183], v[128:131]
	v_mfma_f32_16x16x32_bf16 v[120:123], v[154:157], v[188:191], v[120:123]
	v_mfma_f32_16x16x32_bf16 v[112:115], v[172:175], v[188:191], v[112:115]
	v_mfma_f32_16x16x32_bf16 v[104:107], v[154:157], v[196:199], v[104:107]
	v_mfma_f32_16x16x32_bf16 v[96:99], v[172:175], v[196:199], v[96:99]
	v_mfma_f32_16x16x32_bf16 v[88:91], v[154:157], v[204:207], v[88:91]
	v_mfma_f32_16x16x32_bf16 v[80:83], v[172:175], v[204:207], v[80:83]
	s_setprio 0
	s_barrier
	s_add_i32 s61, s30, s93
	v_lshl_add_u64 v[210:211], s[96:97], 0, v[144:145]
	s_mov_b32 m0, s61
	ds_read_b128 v[176:179], v169 offset:16384
	ds_read_b128 v[180:183], v169 offset:17408
	ds_read_b128 v[184:187], v169 offset:18432
	ds_read_b128 v[188:191], v169 offset:19456
	ds_read_b128 v[192:195], v169 offset:20480
	ds_read_b128 v[196:199], v169 offset:21504
	ds_read_b128 v[200:203], v169 offset:22528
	ds_read_b128 v[204:207], v169 offset:23552
	global_load_lds_dwordx4 v[210:211], off
	v_lshl_add_u64 v[212:213], v[210:211], 0, s[6:7]
	s_add_i32 m0, s61, 0x2000
	s_add_i32 s61, s31, s93
	global_load_lds_dwordx4 v[212:213], off
	v_lshl_add_u64 v[212:213], v[210:211], 0, s[8:9]
	s_mov_b32 m0, s61
	s_nop 0
	global_load_lds_dwordx4 v[212:213], off
	v_lshl_add_u64 v[212:213], v[210:211], 0, s[10:11]
	s_add_i32 m0, s61, 0x2000
	s_nop 0
	global_load_lds_dwordx4 v[212:213], off
	v_lshl_add_u64 v[212:213], s[88:89], 0, v[144:145]
	s_mov_b32 m0, s84
	v_lshl_add_u64 v[214:215], v[212:213], 0, s[6:7]
	global_load_lds_dwordx4 v[212:213], off
	s_mov_b32 m0, s92
	s_nop 0
	global_load_lds_dwordx4 v[214:215], off
	s_waitcnt vmcnt(8)
	s_waitcnt lgkmcnt(0)
	s_barrier
; #define PG8_STAGE(bufoff, gbase, voff) do { _Pragma("unroll") for (int _i = 0; _i < 2; ++_i) \
;         __builtin_amdgcn_global_load_lds((const unsigned*)((const char*)(gbase) + (voff)[_i]), (PG8_LAS unsigned*)(lds + (bufoff) + ldsw + _i * 8192), 16, 0, 0); } while (0)
; #define PG8_LDA(dst, b, h) do { _Pragma("unroll") for (int m = 0; m < 4; ++m) _Pragma("unroll") for (int k = 0; k < 2; ++k) dst[m][k] = *(const PG8_LAS bf16x8*)(lds + PG8_SA(b, h) + aoff + m * 2048 + k * 1024); } while (0)
; #define PG8_LDB(dst, b, h) do { _Pragma("unroll") for (int n = 0; n < 2; ++n) _Pragma("unroll") for (int k = 0; k < 2; ++k) dst[n][k] = *(const PG8_LAS bf16x8*)(lds + PG8_SB(b, h) + boff + n * 2048 + k * 1024); } while (0)
; #define PG8_MMA(ai, bj, At, Bt) do { __builtin_amdgcn_s_setprio(1); _Pragma("unroll") for (int m = 0; m < 4; ++m) _Pragma("unroll") for (int n = 0; n < 2; ++n) _Pragma("unroll") for (int k = 0; k < 2; ++k) \
;         acc[ai][bj][m][n] = __builtin_amdgcn_mfma_f32_16x16x32_bf16(Bt[n][k], At[m][k], acc[ai][bj][m][n], 0, 0, 0); __builtin_amdgcn_s_setprio(0); } while (0)
; #define PG8_WAIT_V(n) asm volatile("s_waitcnt vmcnt(" #n ")" ::: "memory")
; #define PG8_WAIT_L(n) asm volatile("s_waitcnt lgkmcnt(" #n ")" ::: "memory")
; #define PG8_BAR __builtin_amdgcn_s_barrier()
; #define PG8_SCHED __builtin_amdgcn_sched_barrier(0)
; template <class Epi, class Sched, bool ALIGN_EPI = false, bool SP2 = false, bool TA = true>
; __device__ __forceinline__ void gemm_phase(PG8_LAS unsigned char* lds, const Gemm g, const Sched& S, const Epi& E) {
;     ...
;             PG8_LDA(At, 0, 1); PG8_STAGE(PG8_SB(0, 0), b2, voffB); PG8_STAGE(PG8_SB(0, 1), b2 + hstep, voffB); PG8_STAGE(PG8_SA(0, 0), a2, voffA);
;             PG8_WAIT_V(8); PG8_WAIT_L(0); PG8_BAR; PG8_MMA(1, 0, At, B0); PG8_MMA(1, 1, At, B1); PG8_BAR; PG8_SCHED;
;             PG8_LDB(B0, 1, 0); PG8_LDB(B1, 1, 1); PG8_SCHED; PG8_LDA(At, 1, 0); PG8_STAGE(PG8_SA(0, 1), a2 + hstep, voffA);
;             PG8_WAIT_V(8); PG8_WAIT_L(0); PG8_BAR; PG8_MMA(0, 0, At, B0); PG8_MMA(0, 1, At, B1); PG8_BAR; PG8_SCHED;
	s_setprio 1
	s_waitcnt lgkmcnt(0)
	v_mfma_f32_16x16x32_bf16 v[68:71], v[56:59], v[176:179], 0
	v_mfma_f32_16x16x32_bf16 v[52:55], v[72:75], v[176:179], 0
	v_mfma_f32_16x16x32_bf16 v[44:47], v[56:59], v[184:187], 0
	v_mfma_f32_16x16x32_bf16 v[36:39], v[72:75], v[184:187], 0
	v_mfma_f32_16x16x32_bf16 v[28:31], v[56:59], v[192:195], 0
	v_mfma_f32_16x16x32_bf16 v[20:23], v[72:75], v[192:195], 0
	v_mfma_f32_16x16x32_bf16 v[12:15], v[56:59], v[200:203], 0
	v_mfma_f32_16x16x32_bf16 v[4:7], v[72:75], v[200:203], 0
	v_mfma_f32_16x16x32_bf16 v[68:71], v[64:67], v[180:183], v[68:71]
	v_mfma_f32_16x16x32_bf16 v[52:55], v[76:79], v[180:183], v[52:55]
	v_mfma_f32_16x16x32_bf16 v[44:47], v[64:67], v[188:191], v[44:47]
	v_mfma_f32_16x16x32_bf16 v[36:39], v[76:79], v[188:191], v[36:39]
	v_mfma_f32_16x16x32_bf16 v[28:31], v[64:67], v[196:199], v[28:31]
	v_mfma_f32_16x16x32_bf16 v[20:23], v[76:79], v[196:199], v[20:23]
	v_mfma_f32_16x16x32_bf16 v[12:15], v[64:67], v[204:207], v[12:15]
	v_mfma_f32_16x16x32_bf16 v[4:7], v[76:79], v[204:207], v[4:7]
	s_setprio 0
	s_setprio 1
	v_mfma_f32_16x16x32_bf16 v[48:51], v[158:161], v[176:179], 0
	v_mfma_f32_16x16x32_bf16 v[40:43], v[150:153], v[184:187], 0
	v_mfma_f32_16x16x32_bf16 v[32:35], v[158:161], v[184:187], 0
	v_mfma_f32_16x16x32_bf16 v[24:27], v[150:153], v[192:195], 0
	v_mfma_f32_16x16x32_bf16 v[16:19], v[158:161], v[192:195], 0
	v_mfma_f32_16x16x32_bf16 v[8:11], v[150:153], v[200:203], 0
	v_mfma_f32_16x16x32_bf16 v[0:3], v[158:161], v[200:203], 0
	v_mfma_f32_16x16x32_bf16 v[56:59], v[150:153], v[176:179], 0
	v_mfma_f32_16x16x32_bf16 v[48:51], v[172:175], v[180:183], v[48:51]
	v_mfma_f32_16x16x32_bf16 v[40:43], v[154:157], v[188:191], v[40:43]
	v_mfma_f32_16x16x32_bf16 v[32:35], v[172:175], v[188:191], v[32:35]
	v_mfma_f32_16x16x32_bf16 v[24:27], v[154:157], v[196:199], v[24:27]
	v_mfma_f32_16x16x32_bf16 v[16:19], v[172:175], v[196:199], v[16:19]
	v_mfma_f32_16x16x32_bf16 v[8:11], v[154:157], v[204:207], v[8:11]
	v_mfma_f32_16x16x32_bf16 v[0:3], v[172:175], v[204:207], v[0:3]
	v_mfma_f32_16x16x32_bf16 v[56:59], v[154:157], v[180:183], v[56:59]
	s_setprio 0
	s_barrier
	s_add_i32 s61, 0, 0x18000
	s_add_i32 s75, 0, 0x1c000
	v_add_u32_e32 v76, s61, v163
	v_add_u32_e32 v171, s75, v163
	ds_read_b128 v[60:63], v76
	ds_read_b128 v[64:67], v76 offset:1024
	ds_read_b128 v[72:75], v76 offset:2048
	ds_read_b128 v[76:79], v76 offset:3072
	ds_read_b128 v[150:153], v171
	ds_read_b128 v[154:157], v171 offset:1024
	ds_read_b128 v[158:161], v171 offset:2048
	ds_read_b128 v[172:175], v171 offset:3072
	s_mov_b32 m0, s94
	v_lshl_add_u64 v[214:215], v[212:213], 0, s[8:9]
	ds_read_b128 v[176:179], v169 offset:32768
	ds_read_b128 v[180:183], v169 offset:33792
	ds_read_b128 v[184:187], v169 offset:34816
	ds_read_b128 v[188:191], v169 offset:35840
	ds_read_b128 v[192:195], v169 offset:36864
	ds_read_b128 v[196:199], v169 offset:37888
	ds_read_b128 v[200:203], v169 offset:38912
	ds_read_b128 v[204:207], v169 offset:39936
	global_load_lds_dwordx4 v[214:215], off
	v_lshl_add_u64 v[214:215], v[212:213], 0, s[10:11]
	s_mov_b32 m0, s18
	s_nop 0
	global_load_lds_dwordx4 v[214:215], off
	s_waitcnt vmcnt(8)
	s_waitcnt lgkmcnt(0)
	s_barrier
	s_setprio 1
	s_waitcnt lgkmcnt(0)
	v_mfma_f32_16x16x32_bf16 v[140:143], v[60:63], v[176:179], v[140:143]
	v_mfma_f32_16x16x32_bf16 v[136:139], v[72:75], v[176:179], v[136:139]
	v_mfma_f32_16x16x32_bf16 v[124:127], v[60:63], v[184:187], v[124:127]
	v_mfma_f32_16x16x32_bf16 v[116:119], v[72:75], v[184:187], v[116:119]
	v_mfma_f32_16x16x32_bf16 v[108:111], v[60:63], v[192:195], v[108:111]
	v_mfma_f32_16x16x32_bf16 v[100:103], v[72:75], v[192:195], v[100:103]
	v_mfma_f32_16x16x32_bf16 v[92:95], v[60:63], v[200:203], v[92:95]
	v_mfma_f32_16x16x32_bf16 v[84:87], v[72:75], v[200:203], v[84:87]
	v_mfma_f32_16x16x32_bf16 v[140:143], v[64:67], v[180:183], v[140:143]
	v_mfma_f32_16x16x32_bf16 v[136:139], v[76:79], v[180:183], v[136:139]
	v_mfma_f32_16x16x32_bf16 v[124:127], v[64:67], v[188:191], v[124:127]
	v_mfma_f32_16x16x32_bf16 v[116:119], v[76:79], v[188:191], v[116:119]
	v_mfma_f32_16x16x32_bf16 v[108:111], v[64:67], v[196:199], v[108:111]
	v_mfma_f32_16x16x32_bf16 v[100:103], v[76:79], v[196:199], v[100:103]
	v_mfma_f32_16x16x32_bf16 v[92:95], v[64:67], v[204:207], v[92:95]
	v_mfma_f32_16x16x32_bf16 v[84:87], v[76:79], v[204:207], v[84:87]
	s_setprio 0
	s_setprio 1
	v_mfma_f32_16x16x32_bf16 v[132:135], v[150:153], v[176:179], v[132:135]
	v_mfma_f32_16x16x32_bf16 v[128:131], v[158:161], v[176:179], v[128:131]
	v_mfma_f32_16x16x32_bf16 v[120:123], v[150:153], v[184:187], v[120:123]
	v_mfma_f32_16x16x32_bf16 v[112:115], v[158:161], v[184:187], v[112:115]
	v_mfma_f32_16x16x32_bf16 v[104:107], v[150:153], v[192:195], v[104:107]
	v_mfma_f32_16x16x32_bf16 v[96:99], v[158:161], v[192:195], v[96:99]
	v_mfma_f32_16x16x32_bf16 v[88:91], v[150:153], v[200:203], v[88:91]
	v_mfma_f32_16x16x32_bf16 v[80:83], v[158:161], v[200:203], v[80:83]
	v_mfma_f32_16x16x32_bf16 v[132:135], v[154:157], v[180:183], v[132:135]
	v_mfma_f32_16x16x32_bf16 v[128:131], v[172:175], v[180:183], v[128:131]
	v_mfma_f32_16x16x32_bf16 v[120:123], v[154:157], v[188:191], v[120:123]
	v_mfma_f32_16x16x32_bf16 v[112:115], v[172:175], v[188:191], v[112:115]
	v_mfma_f32_16x16x32_bf16 v[104:107], v[154:157], v[196:199], v[104:107]
	v_mfma_f32_16x16x32_bf16 v[96:99], v[172:175], v[196:199], v[96:99]
	v_mfma_f32_16x16x32_bf16 v[88:91], v[154:157], v[204:207], v[88:91]
	v_mfma_f32_16x16x32_bf16 v[80:83], v[172:175], v[204:207], v[80:83]
	s_setprio 0
	s_barrier
; #define PG8_STAGE(bufoff, gbase, voff) do { _Pragma("unroll") for (int _i = 0; _i < 2; ++_i) \
;         __builtin_amdgcn_global_load_lds((const unsigned*)((const char*)(gbase) + (voff)[_i]), (PG8_LAS unsigned*)(lds + (bufoff) + ldsw + _i * 8192), 16, 0, 0); } while (0)
; #define PG8_LDA(dst, b, h) do { _Pragma("unroll") for (int m = 0; m < 4; ++m) _Pragma("unroll") for (int k = 0; k < 2; ++k) dst[m][k] = *(const PG8_LAS bf16x8*)(lds + PG8_SA(b, h) + aoff + m * 2048 + k * 1024); } while (0)
; #define PG8_MMA(ai, bj, At, Bt) do { __builtin_amdgcn_s_setprio(1); _Pragma("unroll") for (int m = 0; m < 4; ++m) _Pragma("unroll") for (int n = 0; n < 2; ++n) _Pragma("unroll") for (int k = 0; k < 2; ++k) \
;         acc[ai][bj][m][n] = __builtin_amdgcn_mfma_f32_16x16x32_bf16(Bt[n][k], At[m][k], acc[ai][bj][m][n], 0, 0, 0); __builtin_amdgcn_s_setprio(0); } while (0)
; #define PG8_WAIT_V(n) asm volatile("s_waitcnt vmcnt(" #n ")" ::: "memory")
; #define PG8_WAIT_L(n) asm volatile("s_waitcnt lgkmcnt(" #n ")" ::: "memory")
; #define PG8_BAR __builtin_amdgcn_s_barrier()
; #define PG8_SCHED __builtin_amdgcn_sched_barrier(0)
; template <class Epi, class Sched, bool ALIGN_EPI = false, bool SP2 = false, bool TA = true>
; __device__ __forceinline__ void gemm_phase(PG8_LAS unsigned char* lds, const Gemm g, const Sched& S, const Epi& E) {
;     ...
;         for (int t = 0; t < nt; t += 2) {
;     ...
;             PG8_LDA(At, 1, 1); PG8_STAGE(PG8_SB(1, 0), b3, voffB); PG8_STAGE(PG8_SB(1, 1), b3 + hstep, voffB); PG8_STAGE(PG8_SA(1, 0), a3, voffA);
;             PG8_WAIT_V(8); PG8_WAIT_L(0); PG8_BAR; PG8_MMA(1, 0, At, B0); PG8_MMA(1, 1, At, B1); PG8_BAR; PG8_SCHED;
	s_add_i32 s61, s61, s93
	v_lshl_add_u64 v[214:215], v[210:211], 0, s[44:45]
	s_mov_b32 m0, s61
	ds_read_b128 v[176:179], v169 offset:49152
	ds_read_b128 v[180:183], v169 offset:50176
	ds_read_b128 v[184:187], v169 offset:51200
	ds_read_b128 v[188:191], v169 offset:52224
	ds_read_b128 v[192:195], v169 offset:53248
	ds_read_b128 v[196:199], v169 offset:54272
	ds_read_b128 v[200:203], v169 offset:55296
	ds_read_b128 v[204:207], v169 offset:56320
	global_load_lds_dwordx4 v[214:215], off
	v_lshl_add_u64 v[214:215], v[210:211], 0, s[46:47]
	s_add_i32 m0, s61, 0x2000
	s_add_i32 s61, s75, s93
	global_load_lds_dwordx4 v[214:215], off
	v_lshl_add_u64 v[214:215], v[210:211], 0, s[48:49]
	s_mov_b32 m0, s61
	v_lshl_add_u64 v[210:211], v[210:211], 0, s[50:51]
	global_load_lds_dwordx4 v[214:215], off
	s_add_i32 m0, s61, 0x2000
	s_nop 0
	global_load_lds_dwordx4 v[210:211], off
	v_lshl_add_u64 v[210:211], v[212:213], 0, s[44:45]
	s_mov_b32 m0, s19
	s_nop 0
	global_load_lds_dwordx4 v[210:211], off
	v_lshl_add_u64 v[210:211], v[212:213], 0, s[46:47]
	s_mov_b32 m0, s21
	s_nop 0
	global_load_lds_dwordx4 v[210:211], off
	s_waitcnt vmcnt(8)
	s_waitcnt lgkmcnt(0)
	s_barrier
	s_setprio 1
	s_waitcnt lgkmcnt(0)
	v_mfma_f32_16x16x32_bf16 v[68:71], v[60:63], v[176:179], v[68:71]
	v_mfma_f32_16x16x32_bf16 v[52:55], v[72:75], v[176:179], v[52:55]
	v_mfma_f32_16x16x32_bf16 v[44:47], v[60:63], v[184:187], v[44:47]
	v_mfma_f32_16x16x32_bf16 v[36:39], v[72:75], v[184:187], v[36:39]
	v_mfma_f32_16x16x32_bf16 v[28:31], v[60:63], v[192:195], v[28:31]
	v_mfma_f32_16x16x32_bf16 v[20:23], v[72:75], v[192:195], v[20:23]
	v_mfma_f32_16x16x32_bf16 v[12:15], v[60:63], v[200:203], v[12:15]
	v_mfma_f32_16x16x32_bf16 v[4:7], v[72:75], v[200:203], v[4:7]
	v_mfma_f32_16x16x32_bf16 v[68:71], v[64:67], v[180:183], v[68:71]
	v_mfma_f32_16x16x32_bf16 v[52:55], v[76:79], v[180:183], v[52:55]
	v_mfma_f32_16x16x32_bf16 v[44:47], v[64:67], v[188:191], v[44:47]
	v_mfma_f32_16x16x32_bf16 v[36:39], v[76:79], v[188:191], v[36:39]
	v_mfma_f32_16x16x32_bf16 v[28:31], v[64:67], v[196:199], v[28:31]
	v_mfma_f32_16x16x32_bf16 v[20:23], v[76:79], v[196:199], v[20:23]
	v_mfma_f32_16x16x32_bf16 v[12:15], v[64:67], v[204:207], v[12:15]
	v_mfma_f32_16x16x32_bf16 v[4:7], v[76:79], v[204:207], v[4:7]
	s_setprio 0
	s_setprio 1
	v_mfma_f32_16x16x32_bf16 v[56:59], v[150:153], v[176:179], v[56:59]
	v_mfma_f32_16x16x32_bf16 v[48:51], v[158:161], v[176:179], v[48:51]
	v_mfma_f32_16x16x32_bf16 v[40:43], v[150:153], v[184:187], v[40:43]
	v_mfma_f32_16x16x32_bf16 v[32:35], v[158:161], v[184:187], v[32:35]
	v_mfma_f32_16x16x32_bf16 v[24:27], v[150:153], v[192:195], v[24:27]
	v_mfma_f32_16x16x32_bf16 v[16:19], v[158:161], v[192:195], v[16:19]
	v_mfma_f32_16x16x32_bf16 v[8:11], v[150:153], v[200:203], v[8:11]
	v_mfma_f32_16x16x32_bf16 v[0:3], v[158:161], v[200:203], v[0:3]
	v_mfma_f32_16x16x32_bf16 v[60:63], v[154:157], v[180:183], v[56:59]
	v_mfma_f32_16x16x32_bf16 v[48:51], v[172:175], v[180:183], v[48:51]
	v_mfma_f32_16x16x32_bf16 v[40:43], v[154:157], v[188:191], v[40:43]
	v_mfma_f32_16x16x32_bf16 v[32:35], v[172:175], v[188:191], v[32:35]
	v_mfma_f32_16x16x32_bf16 v[24:27], v[154:157], v[196:199], v[24:27]
	v_mfma_f32_16x16x32_bf16 v[16:19], v[172:175], v[196:199], v[16:19]
	v_mfma_f32_16x16x32_bf16 v[8:11], v[154:157], v[204:207], v[8:11]
	v_mfma_f32_16x16x32_bf16 v[0:3], v[172:175], v[204:207], v[0:3]
	s_setprio 0
	s_barrier
	s_add_i32 s59, s59, 2
	s_add_u32 s86, s86, 0x8000
	s_addc_u32 s87, s87, 0
	s_add_u32 s42, s42, 0x8000
	s_addc_u32 s43, s43, 0
	s_cmp_gt_u32 s59, 13
